# also the WO (cross-attention output weight) conversion items moved from the P0 prologue to idle waves 6,7 at seams 0 and 1
# speedup vs baseline: 1.0117x; 1.0028x over previous
; #define LAS __attribute__((address_space(3)))
; __device__ __forceinline__ TrItem tr_decode(int it, const float* const* in, unsigned char* ws, int lane) {
;     int r = it, kind = 0, ndb = 32, N = D, K = D; const float *W, *W2 = nullptr, *gain = nullptr; bf16_t* WT; bool nts = false, woh = false;
;     if (r < 5632) { kind = 1; W = in[3]; W2 = in[4]; N = FF; ndb = 176; gain = in[2]; WT = (bf16_t*)(ws + WS_W1GU); }
;     else if ((r -= 5632) < 2816) { W = in[5]; K = FF; WT = (bf16_t*)(ws + WS_W1D); }
;     else if ((r -= 2816) < 2688) { kind = 2; W = in[7]; N = INC; ndb = 84; gain = in[6]; WT = (bf16_t*)(ws + WS_WIN); nts = true; }
;     else if ((r -= 2688) < 1024) { W = in[10]; WT = (bf16_t*)(ws + WS_WOUT); nts = true; }
;     else if ((r -= 1024) < 1024) { W = in[13]; gain = in[11]; WT = (bf16_t*)(ws + WS_WQ); nts = true; }
;     else if ((r -= 1024) < 2048) { W = in[14]; N = 2 * D; ndb = 64; gain = in[12]; WT = (bf16_t*)(ws + WS_WKV); }
;     else if ((r -= 2048) < 1024) { W = in[15]; WT = (bf16_t*)(ws + WS_WO); nts = true; woh = true; }
;     else if ((r -= 1024) < 5632) { kind = 1; W = in[17]; W2 = in[18]; N = FF; ndb = 176; gain = in[16]; WT = (bf16_t*)(ws + WS_W2GU); nts = true; }
;     else { r -= 5632; W = in[19]; K = FF; WT = (bf16_t*)(ws + WS_W2D); }
;     __device__ __forceinline__ int count() const { return (e0 - b0) + (e1 - b1) + (e2 - b2); }
; __device__ __forceinline__ void tr_all(const float* const* in, unsigned char* ws, LAS float* scr, int gw, int ngw, int lane, const TrRanges rg) {
;     const int TR_CNT = rg.count();
;     if (gw >= TR_CNT) return;
;     TrItem cur = tr_decode(rg.item(gw), in, ws, lane);
.LBB0_158:
	s_andn2_b64 vcc, exec, s[0:1]
	s_cbranch_vccnz .LBB0_280
	s_cmpk_gt_i32 s4, 0x7ff
	s_cbranch_scc1 .LBB0_271
	s_cmpk_lt_i32 s4, 0x1000
	s_movk_i32 s0, 0x3380
	s_cselect_b32 s0, s0, 0x3380
	s_add_i32 s5, s4, s0
	s_cmpk_lt_i32 s5, 0x1600
	s_mov_b64 s[22:23], -1
	s_cbranch_scc1 .LBB0_168
	s_cmpk_gt_u32 s5, 0x20ff
	s_cbranch_scc0 .LBB0_169
	s_cmpk_gt_u32 s5, 0x2b7f
	s_cbranch_scc0 .LBB0_170
	s_cmpk_gt_u32 s5, 0x2f7f
	s_cbranch_scc0 .LBB0_171
	s_cmpk_gt_u32 s5, 0x337f
	s_cbranch_scc0 .LBB0_172
	s_cmpk_gt_u32 s5, 0x3b7f
	s_cbranch_scc0 .LBB0_173
	s_cmpk_gt_u32 s5, 0x3f7f
	s_mov_b64 s[26:27], -1
	s_cbranch_scc0 .LBB0_174
	v_readlane_b32 s40, v254, 4
	v_readlane_b32 s41, v254, 5
	v_readlane_b32 s42, v254, 6
	v_readlane_b32 s43, v254, 7
	v_readlane_b32 s44, v254, 8
	v_readlane_b32 s45, v254, 9
	s_add_i32 s34, s5, 0xffffc080
	s_mov_b64 s[18:19], 0
	v_readlane_b32 s46, v254, 10
	v_readlane_b32 s47, v254, 11
	s_mov_b64 s[16:17], s[42:43]
	s_mov_b64 s[0:1], s[44:45]
	s_mov_b64 s[14:15], s[40:41]
	s_branch .LBB0_175

; __device__ __forceinline__ TrItem tr_decode(int it, const float* const* in, unsigned char* ws, int lane) {
;     int r = it, kind = 0, ndb = 32, N = D, K = D; const float *W, *W2 = nullptr, *gain = nullptr; bf16_t* WT; bool nts = false, woh = false;
;     if (r < 5632) { kind = 1; W = in[3]; W2 = in[4]; N = FF; ndb = 176; gain = in[2]; WT = (bf16_t*)(ws + WS_W1GU); }
;     else if ((r -= 5632) < 2816) { W = in[5]; K = FF; WT = (bf16_t*)(ws + WS_W1D); }
;     else if ((r -= 2816) < 2688) { kind = 2; W = in[7]; N = INC; ndb = 84; gain = in[6]; WT = (bf16_t*)(ws + WS_WIN); nts = true; }
;     else if ((r -= 2688) < 1024) { W = in[10]; WT = (bf16_t*)(ws + WS_WOUT); nts = true; }
;     else if ((r -= 1024) < 1024) { W = in[13]; gain = in[11]; WT = (bf16_t*)(ws + WS_WQ); nts = true; }
;     else if ((r -= 1024) < 2048) { W = in[14]; N = 2 * D; ndb = 64; gain = in[12]; WT = (bf16_t*)(ws + WS_WKV); }
;     else if ((r -= 2048) < 1024) { W = in[15]; WT = (bf16_t*)(ws + WS_WO); nts = true; woh = true; }
;     else if ((r -= 1024) < 5632) { kind = 1; W = in[17]; W2 = in[18]; N = FF; ndb = 176; gain = in[16]; WT = (bf16_t*)(ws + WS_W2GU); nts = true; }
;     else { r -= 5632; W = in[19]; K = FF; WT = (bf16_t*)(ws + WS_W2D); }
; __device__ __forceinline__ void tr_all(const float* const* in, unsigned char* ws, LAS float* scr, int gw, int ngw, int lane, const TrRanges rg) {
;     ...
;     for (int it = gw; it < TR_CNT; it += ngw) {
;         const int nit = it + ngw; const bool hn = nit < TR_CNT;
;         TrItem nx = cur; f32x4 w[16];
;         if (hn) { nx = tr_decode(rg.item(nit), in, ws, lane);
.LBB0_217:
	s_add_i32 s5, s18, s2
	s_cmpk_lt_i32 s5, 0x800
	s_cselect_b64 s[16:17], -1, 0
	s_cmpk_gt_i32 s5, 0x7ff
	s_cselect_b64 s[14:15], -1, 0
	s_and_b64 vcc, exec, s[14:15]
	v_mov_b64_e32 v[148:149], v[146:147]
	v_mov_b64_e32 v[150:151], v[142:143]
	s_mov_b32 s33, s0
	s_cbranch_vccnz .LBB0_266
	s_cmpk_lt_i32 s5, 0x1000
	s_movk_i32 s19, 0x3380
	s_cselect_b32 s19, s19, 0x3380
	s_add_i32 s26, s2, s19
	s_add_i32 s42, s19, s5
	s_add_i32 s26, s26, s18
	s_cmpk_lt_i32 s26, 0x1600
	s_mov_b64 s[28:29], -1
	s_cbranch_scc1 .LBB0_228
	s_cmpk_gt_u32 s26, 0x20ff
	s_cbranch_scc0 .LBB0_229
	s_cmpk_gt_u32 s26, 0x2b7f
	s_cbranch_scc0 .LBB0_230
	s_cmpk_gt_u32 s26, 0x2f7f
	s_cbranch_scc0 .LBB0_231
	s_cmpk_gt_u32 s26, 0x337f
	s_cbranch_scc0 .LBB0_232
	s_cmpk_gt_u32 s26, 0x3b7f
	s_cbranch_scc0 .LBB0_233
	v_readlane_b32 s48, v254, 18
	v_readlane_b32 s62, v254, 32
	v_readlane_b32 s63, v254, 33
	s_cmpk_gt_u32 s26, 0x3f7f
	s_mov_b64 s[34:35], -1
	s_mov_b64 s[18:19], s[62:63]
	s_mov_b64 s[20:21], -1
	v_readlane_b32 s49, v254, 19
	v_readlane_b32 s50, v254, 20
	v_readlane_b32 s51, v254, 21
	v_readlane_b32 s52, v254, 22
	v_readlane_b32 s53, v254, 23
	v_readlane_b32 s54, v254, 24
	v_readlane_b32 s55, v254, 25
	v_readlane_b32 s56, v254, 26
	v_readlane_b32 s57, v254, 27
	v_readlane_b32 s58, v254, 28
	v_readlane_b32 s59, v254, 29
	v_readlane_b32 s60, v254, 30
	v_readlane_b32 s61, v254, 31
	s_cbranch_scc0 .LBB0_226
	v_readlane_b32 s48, v254, 4
	v_readlane_b32 s49, v254, 5
	v_readlane_b32 s50, v254, 6
	v_readlane_b32 s51, v254, 7
	v_readlane_b32 s52, v254, 8
	v_readlane_b32 s53, v254, 9
	s_add_i32 s44, s26, 0xffffc080
	s_mov_b64 s[20:21], 0
	v_readlane_b32 s54, v254, 10
	v_readlane_b32 s55, v254, 11
	s_mov_b64 s[18:19], s[50:51]
	s_mov_b64 s[24:25], s[52:53]
	s_mov_b64 s[22:23], s[48:49]

; #define LAS __attribute__((address_space(3)))
; #define TR_LOAD(p) __builtin_nontemporal_load(p)
; __device__ __forceinline__ TrItem tr_decode(int it, const float* const* in, unsigned char* ws, int lane) {
;     ...
;     const int rh = r >> 3, rl = r & 7, nq = ndb >> DL, kbh = rh / nq, dbh = rh - kbh * nq;
;     const int kb = (kbh << KL) + (rl >> DL), db = (dbh << DL) + (rl & ((1 << DL) - 1)), d0 = db * 64, k0 = kb * 64;
;     ...
;     const int kb = r / ndb, db = r - kb * ndb, d0 = db * 64, k0 = kb * 64;
;     ...
;     const int blk = d0 + 32 * ((lane & 15) >> 3);
;     const float* src = W; int s0 = blk;
;     if (kind == 1) { const int pn = blk >> 8, bj = (blk >> 7) & 1, o = blk & 127; src = bj ? W2 : W; s0 = pn * 128 + o; }
;     else if (kind == 2) s0 = win_src(blk);
;     TrItem t; t.src = src + (size_t)(k0 + (lane >> 4)) * N + s0 + 4 * (lane & 7); t.gain = gain ? gain + k0 + 8 * (lane & 7) : nullptr;
;     t.dst = WT + (size_t)(d0 + (lane >> 3)) * K + k0 + 8 * (lane & 7); t.N = N; t.K = K; t.nts = nts && TR_NTS;
; __device__ __forceinline__ void tr_all(const float* const* in, unsigned char* ws, LAS float* scr, int gw, int ngw, int lane, const TrRanges rg) {
;     ...
;     for (int i = 0; i < 16; ++i) v[i] = TR_LOAD((const f32x4*)(cur.src + (size_t)(4 * i) * cur.N));
;     for (int it = gw; it < TR_CNT; it += ngw) {
;         const int nit = it + ngw; const bool hn = nit < TR_CNT;
;         TrItem nx = cur; f32x4 w[16];
;         if (hn) { nx = tr_decode(rg.item(nit), in, ws, lane);
; #pragma unroll
;             for (int i = 0; i < 16; ++i) w[i] = TR_LOAD((const f32x4*)(nx.src + (size_t)(4 * i) * nx.N)); }
;         LAS float* wp = scr + (lane >> 4) * 65 + 4 * (lane & 15);
; #pragma unroll
;         for (int i = 0; i < 16; ++i) { wp[(4 * i) * 65 + 0] = v[i][0]; wp[(4 * i) * 65 + 1] = v[i][1]; wp[(4 * i) * 65 + 2] = v[i][2]; wp[(4 * i) * 65 + 3] = v[i][3]; }
.Lseam_cv_0:
	s_cmp_lt_u32 s98, 2
	s_cbranch_scc1 .LBB0_339
	s_cmp_gt_u32 s98, 5
	s_cbranch_scc1 .Lseam_cv_0_1
	s_mov_b64 exec, -1
	s_lshl_b32 s99, s87, 2
	s_add_i32 s99, s99, s98
	s_add_i32 s99, s99, 0x5fe
	s_lshr_b32 s100, s99, 3
	s_mul_i32 s101, s100, 0x5d2
	s_lshr_b32 s101, s101, 16
	s_mul_i32 vcc_lo, s101, 44
	s_sub_i32 s100, s100, vcc_lo
	s_and_b32 vcc_lo, s99, 7
	s_lshr_b32 vcc_hi, vcc_lo, 2
	s_lshl_b32 s101, s101, 1
	s_add_i32 s101, s101, vcc_hi
	s_and_b32 vcc_lo, vcc_lo, 3
	s_lshl_b32 s100, s100, 2
	s_add_i32 s100, s100, vcc_lo
	s_lshl_b32 s101, s101, 6
	s_lshl_b32 s100, s100, 6
	v_and_b32_e32 v66, 63, v1
	v_lshrrev_b32_e32 v67, 4, v66
	v_and_b32_e32 v68, 15, v66
	v_and_b32_e32 v73, 7, v66
	v_lshrrev_b32_e32 v72, 3, v66
	s_mul_i32 s99, s98, 0x4100
	v_mul_u32_u24_e32 v70, 0x104, v67
	v_lshl_add_u32 v70, v68, 4, v70
	v_add_u32_e32 v70, s99, v70
	v_mul_u32_u24_e32 v71, 0x820, v73
	v_lshl_add_u32 v71, v72, 2, v71
	v_add_u32_e32 v71, s99, v71
	s_mul_i32 s99, s101, 0x1600
	s_lshr_b32 vcc_lo, s100, 8
	s_lshl_b32 vcc_lo, vcc_lo, 7
	s_add_i32 s99, s99, vcc_lo
	s_and_b32 vcc_lo, s100, 0x7f
	s_add_i32 s99, s99, vcc_lo
	s_lshl_b32 s99, s99, 2
	v_mul_u32_u24_e32 v69, 0x5800, v67
	v_lshl_add_u32 v69, v68, 4, v69
	v_add_u32_e32 v69, s99, v69
	s_lshl_b32 s99, s100, 12
	s_lshl_b32 vcc_lo, s101, 1
	s_add_i32 s99, s99, vcc_lo
	v_lshlrev_b32_e32 v72, 12, v72
	v_lshl_add_u32 v72, v73, 4, v72
	v_add_u32_e32 v72, s99, v72
	s_lshl_b32 s99, s101, 2
	v_lshlrev_b32_e32 v73, 5, v73
	v_add_u32_e32 v73, s99, v73
	s_nop 0
	s_bitcmp1_b32 s100, 7
	v_readlane_b32 s100, v254, 6
	v_readlane_b32 s101, v254, 7
	v_readlane_b32 s98, v254, 8
	v_readlane_b32 s99, v254, 9
	s_nop 3
	s_cselect_b32 s100, s98, s100
	s_cselect_b32 s101, s99, s101
	v_readlane_b32 s98, v254, 4
	v_readlane_b32 s99, v254, 5
	global_load_dwordx4 v[2:5], v69, s[100:101] nt
	v_add_u32_e32 v68, 0x16000, v69
	global_load_dwordx4 v[6:9], v68, s[100:101] nt
	v_add_u32_e32 v67, 0x2c000, v69
	global_load_dwordx4 v[10:13], v67, s[100:101] nt
	v_add_u32_e32 v68, 0x42000, v69
	global_load_dwordx4 v[14:17], v68, s[100:101] nt
	v_add_u32_e32 v67, 0x58000, v69
	global_load_dwordx4 v[18:21], v67, s[100:101] nt
	v_add_u32_e32 v68, 0x6e000, v69
	global_load_dwordx4 v[22:25], v68, s[100:101] nt
	v_add_u32_e32 v67, 0x84000, v69
	global_load_dwordx4 v[26:29], v67, s[100:101] nt
	v_add_u32_e32 v68, 0x9a000, v69
	global_load_dwordx4 v[30:33], v68, s[100:101] nt
	v_add_u32_e32 v67, 0xb0000, v69
	global_load_dwordx4 v[34:37], v67, s[100:101] nt
	v_add_u32_e32 v68, 0xc6000, v69
	global_load_dwordx4 v[38:41], v68, s[100:101] nt
	v_add_u32_e32 v67, 0xdc000, v69
	global_load_dwordx4 v[42:45], v67, s[100:101] nt
	v_add_u32_e32 v68, 0xf2000, v69
	global_load_dwordx4 v[46:49], v68, s[100:101] nt
	v_add_u32_e32 v67, 0x108000, v69
	global_load_dwordx4 v[50:53], v67, s[100:101] nt
	v_add_u32_e32 v68, 0x11e000, v69
	global_load_dwordx4 v[54:57], v68, s[100:101] nt
	v_add_u32_e32 v67, 0x134000, v69
	global_load_dwordx4 v[58:61], v67, s[100:101] nt
	v_add_u32_e32 v68, 0x14a000, v69
	global_load_dwordx4 v[62:65], v68, s[100:101] nt
	global_load_dwordx4 v[74:77], v73, s[98:99]
	global_load_dwordx4 v[78:81], v73, s[98:99] offset:16
	s_waitcnt vmcnt(17)
	ds_write_b32 v70, v2
	ds_write_b32 v70, v3 offset:4
	ds_write_b32 v70, v4 offset:8
	ds_write_b32 v70, v5 offset:12
	s_waitcnt vmcnt(16)
	ds_write_b32 v70, v6 offset:1040
	ds_write_b32 v70, v7 offset:1044
	ds_write_b32 v70, v8 offset:1048
	ds_write_b32 v70, v9 offset:1052
	s_waitcnt vmcnt(15)
	ds_write_b32 v70, v10 offset:2080
	ds_write_b32 v70, v11 offset:2084
	ds_write_b32 v70, v12 offset:2088
	ds_write_b32 v70, v13 offset:2092
	s_waitcnt vmcnt(14)
	ds_write_b32 v70, v14 offset:3120
	ds_write_b32 v70, v15 offset:3124
	ds_write_b32 v70, v16 offset:3128
	ds_write_b32 v70, v17 offset:3132
	s_waitcnt vmcnt(13)
	ds_write_b32 v70, v18 offset:4160
	ds_write_b32 v70, v19 offset:4164
	ds_write_b32 v70, v20 offset:4168
	ds_write_b32 v70, v21 offset:4172
	s_waitcnt vmcnt(12)
	ds_write_b32 v70, v22 offset:5200
	ds_write_b32 v70, v23 offset:5204
	ds_write_b32 v70, v24 offset:5208
	ds_write_b32 v70, v25 offset:5212
	s_waitcnt vmcnt(11)
	ds_write_b32 v70, v26 offset:6240
	ds_write_b32 v70, v27 offset:6244
	ds_write_b32 v70, v28 offset:6248
	ds_write_b32 v70, v29 offset:6252
	s_waitcnt vmcnt(10)
	ds_write_b32 v70, v30 offset:7280
	ds_write_b32 v70, v31 offset:7284
	ds_write_b32 v70, v32 offset:7288
	ds_write_b32 v70, v33 offset:7292
	s_waitcnt vmcnt(9)
	ds_write_b32 v70, v34 offset:8320
	ds_write_b32 v70, v35 offset:8324
	ds_write_b32 v70, v36 offset:8328
	ds_write_b32 v70, v37 offset:8332
	s_waitcnt vmcnt(8)
	ds_write_b32 v70, v38 offset:9360
	ds_write_b32 v70, v39 offset:9364
	ds_write_b32 v70, v40 offset:9368
	ds_write_b32 v70, v41 offset:9372
	s_waitcnt vmcnt(7)
	ds_write_b32 v70, v42 offset:10400
	ds_write_b32 v70, v43 offset:10404
	ds_write_b32 v70, v44 offset:10408
	ds_write_b32 v70, v45 offset:10412
	s_waitcnt vmcnt(6)
	ds_write_b32 v70, v46 offset:11440
	ds_write_b32 v70, v47 offset:11444
	ds_write_b32 v70, v48 offset:11448
	ds_write_b32 v70, v49 offset:11452
	s_waitcnt vmcnt(5)
	ds_write_b32 v70, v50 offset:12480
	ds_write_b32 v70, v51 offset:12484
	ds_write_b32 v70, v52 offset:12488
	ds_write_b32 v70, v53 offset:12492
	s_waitcnt vmcnt(4)
	ds_write_b32 v70, v54 offset:13520
	ds_write_b32 v70, v55 offset:13524
	ds_write_b32 v70, v56 offset:13528
	ds_write_b32 v70, v57 offset:13532
	s_waitcnt vmcnt(3)
	ds_write_b32 v70, v58 offset:14560
	ds_write_b32 v70, v59 offset:14564
	ds_write_b32 v70, v60 offset:14568
	ds_write_b32 v70, v61 offset:14572
	s_waitcnt vmcnt(2)
; #define LAS __attribute__((address_space(3)))
; __device__ __forceinline__ unsigned cvtpk(float lo, float hi) { f32x2_t v = {lo, hi}; bf16x2_t b = __builtin_convertvector(v, bf16x2_t); return __builtin_bit_cast(unsigned, b); }
; __device__ __forceinline__ void tr_all(const float* const* in, unsigned char* ws, LAS float* scr, int gw, int ngw, int lane, const TrRanges rg) {
;     ...
;         const LAS float* rp = scr + (8 * (lane & 7)) * 65 + (lane >> 3);
; #pragma unroll
;         for (int j = 0; j < 8; ++j) { const LAS float* s = rp + 8 * j;
;             u32x4 o; o.x = cvtpk(s[0 * 65] * g0[0], s[1 * 65] * g0[1]); o.y = cvtpk(s[2 * 65] * g0[2], s[3 * 65] * g0[3]);
;             o.z = cvtpk(s[4 * 65] * g1[0], s[5 * 65] * g1[1]); o.w = cvtpk(s[6 * 65] * g1[2], s[7 * 65] * g1[3]);
;             if (cur.nts) __builtin_nontemporal_store(o, (u32x4*)(cur.dst + (size_t)(8 * j) * cur.K)); else *(u32x4*)(cur.dst + (size_t)(8 * j) * cur.K) = o; }
;         asm volatile("s_waitcnt lgkmcnt(0)" ::: "memory");
	ds_write_b32 v70, v62 offset:15600
	ds_write_b32 v70, v63 offset:15604
	ds_write_b32 v70, v64 offset:15608
	ds_write_b32 v70, v65 offset:15612
	s_add_u32 s100, s84, 0x8f00000
	s_addc_u32 s101, s85, 0
	s_waitcnt vmcnt(0) lgkmcnt(0)
	ds_read_b32 v2, v71
	ds_read_b32 v3, v71 offset:260
	ds_read_b32 v4, v71 offset:520
	ds_read_b32 v5, v71 offset:780
	ds_read_b32 v6, v71 offset:1040
	ds_read_b32 v7, v71 offset:1300
	ds_read_b32 v8, v71 offset:1560
	ds_read_b32 v9, v71 offset:1820
	ds_read_b32 v10, v71 offset:32
	ds_read_b32 v11, v71 offset:292
	ds_read_b32 v12, v71 offset:552
	ds_read_b32 v13, v71 offset:812
	ds_read_b32 v14, v71 offset:1072
	ds_read_b32 v15, v71 offset:1332
	ds_read_b32 v16, v71 offset:1592
	ds_read_b32 v17, v71 offset:1852
	ds_read_b32 v18, v71 offset:64
	ds_read_b32 v19, v71 offset:324
	ds_read_b32 v20, v71 offset:584
	ds_read_b32 v21, v71 offset:844
	ds_read_b32 v22, v71 offset:1104
	ds_read_b32 v23, v71 offset:1364
	ds_read_b32 v24, v71 offset:1624
	ds_read_b32 v25, v71 offset:1884
	ds_read_b32 v26, v71 offset:96
	ds_read_b32 v27, v71 offset:356
	ds_read_b32 v28, v71 offset:616
	ds_read_b32 v29, v71 offset:876
	ds_read_b32 v30, v71 offset:1136
	ds_read_b32 v31, v71 offset:1396
	ds_read_b32 v32, v71 offset:1656
	ds_read_b32 v33, v71 offset:1916
	ds_read_b32 v34, v71 offset:128
	ds_read_b32 v35, v71 offset:388
	ds_read_b32 v36, v71 offset:648
	ds_read_b32 v37, v71 offset:908
	ds_read_b32 v38, v71 offset:1168
	ds_read_b32 v39, v71 offset:1428
	ds_read_b32 v40, v71 offset:1688
	ds_read_b32 v41, v71 offset:1948
	ds_read_b32 v42, v71 offset:160
	ds_read_b32 v43, v71 offset:420
	ds_read_b32 v44, v71 offset:680
	ds_read_b32 v45, v71 offset:940
	ds_read_b32 v46, v71 offset:1200
	ds_read_b32 v47, v71 offset:1460
	ds_read_b32 v48, v71 offset:1720
	ds_read_b32 v49, v71 offset:1980
	ds_read_b32 v50, v71 offset:192
	ds_read_b32 v51, v71 offset:452
	ds_read_b32 v52, v71 offset:712
	ds_read_b32 v53, v71 offset:972
	ds_read_b32 v54, v71 offset:1232
	ds_read_b32 v55, v71 offset:1492
	ds_read_b32 v56, v71 offset:1752
	ds_read_b32 v57, v71 offset:2012
	ds_read_b32 v58, v71 offset:224
	ds_read_b32 v59, v71 offset:484
	ds_read_b32 v60, v71 offset:744
	ds_read_b32 v61, v71 offset:1004
	ds_read_b32 v62, v71 offset:1264
	ds_read_b32 v63, v71 offset:1524
	ds_read_b32 v64, v71 offset:1784
	ds_read_b32 v65, v71 offset:2044
	s_waitcnt lgkmcnt(15)
	v_mul_f32_e32 v2, v2, v74
	v_mul_f32_e32 v3, v3, v75
	v_mul_f32_e32 v4, v4, v76
	v_mul_f32_e32 v5, v5, v77
	v_mul_f32_e32 v6, v6, v78
	v_mul_f32_e32 v7, v7, v79
	v_mul_f32_e32 v8, v8, v80
	v_mul_f32_e32 v9, v9, v81
	v_cvt_pk_bf16_f32 v192, v2, v3
	v_cvt_pk_bf16_f32 v193, v4, v5
	v_cvt_pk_bf16_f32 v194, v6, v7
	v_cvt_pk_bf16_f32 v195, v8, v9
	global_store_dwordx4 v72, v[192:195], s[100:101] nt
	s_waitcnt lgkmcnt(15)
	v_mul_f32_e32 v10, v10, v74
	v_mul_f32_e32 v11, v11, v75
	v_mul_f32_e32 v12, v12, v76
	v_mul_f32_e32 v13, v13, v77
	v_mul_f32_e32 v14, v14, v78
	v_mul_f32_e32 v15, v15, v79
	v_mul_f32_e32 v16, v16, v80
	v_mul_f32_e32 v17, v17, v81
	v_cvt_pk_bf16_f32 v196, v10, v11
	v_cvt_pk_bf16_f32 v197, v12, v13
	v_cvt_pk_bf16_f32 v198, v14, v15
	v_cvt_pk_bf16_f32 v199, v16, v17
	v_add_u32_e32 v68, 0x8000, v72
	global_store_dwordx4 v68, v[196:199], s[100:101] nt
	s_waitcnt lgkmcnt(15)
	v_mul_f32_e32 v18, v18, v74
	v_mul_f32_e32 v19, v19, v75
	v_mul_f32_e32 v20, v20, v76
	v_mul_f32_e32 v21, v21, v77
	v_mul_f32_e32 v22, v22, v78
	v_mul_f32_e32 v23, v23, v79
	v_mul_f32_e32 v24, v24, v80
	v_mul_f32_e32 v25, v25, v81
	v_cvt_pk_bf16_f32 v200, v18, v19
	v_cvt_pk_bf16_f32 v201, v20, v21
	v_cvt_pk_bf16_f32 v202, v22, v23
	v_cvt_pk_bf16_f32 v203, v24, v25
	v_add_u32_e32 v67, 0x10000, v72
	global_store_dwordx4 v67, v[200:203], s[100:101] nt
	s_waitcnt lgkmcnt(15)
	v_mul_f32_e32 v26, v26, v74
	v_mul_f32_e32 v27, v27, v75
	v_mul_f32_e32 v28, v28, v76
	v_mul_f32_e32 v29, v29, v77
	v_mul_f32_e32 v30, v30, v78
	v_mul_f32_e32 v31, v31, v79
	v_mul_f32_e32 v32, v32, v80
	v_mul_f32_e32 v33, v33, v81
	v_cvt_pk_bf16_f32 v204, v26, v27
	v_cvt_pk_bf16_f32 v205, v28, v29
	v_cvt_pk_bf16_f32 v206, v30, v31
	v_cvt_pk_bf16_f32 v207, v32, v33
	v_add_u32_e32 v68, 0x18000, v72
	global_store_dwordx4 v68, v[204:207], s[100:101] nt
	s_waitcnt lgkmcnt(15)
	v_mul_f32_e32 v34, v34, v74
	v_mul_f32_e32 v35, v35, v75
	v_mul_f32_e32 v36, v36, v76
	v_mul_f32_e32 v37, v37, v77
	v_mul_f32_e32 v38, v38, v78
	v_mul_f32_e32 v39, v39, v79
	v_mul_f32_e32 v40, v40, v80
	v_mul_f32_e32 v41, v41, v81
	v_cvt_pk_bf16_f32 v208, v34, v35
	v_cvt_pk_bf16_f32 v209, v36, v37
	v_cvt_pk_bf16_f32 v210, v38, v39
	v_cvt_pk_bf16_f32 v211, v40, v41
	v_add_u32_e32 v67, 0x20000, v72
	global_store_dwordx4 v67, v[208:211], s[100:101] nt
	s_waitcnt lgkmcnt(15)
	v_mul_f32_e32 v42, v42, v74
	v_mul_f32_e32 v43, v43, v75
	v_mul_f32_e32 v44, v44, v76
	v_mul_f32_e32 v45, v45, v77
	v_mul_f32_e32 v46, v46, v78
	v_mul_f32_e32 v47, v47, v79
	v_mul_f32_e32 v48, v48, v80
	v_mul_f32_e32 v49, v49, v81
	v_cvt_pk_bf16_f32 v212, v42, v43
	v_cvt_pk_bf16_f32 v213, v44, v45
	v_cvt_pk_bf16_f32 v214, v46, v47
	v_cvt_pk_bf16_f32 v215, v48, v49
	v_add_u32_e32 v68, 0x28000, v72
	global_store_dwordx4 v68, v[212:215], s[100:101] nt
	s_waitcnt lgkmcnt(8)
	v_mul_f32_e32 v50, v50, v74
	v_mul_f32_e32 v51, v51, v75
	v_mul_f32_e32 v52, v52, v76
	v_mul_f32_e32 v53, v53, v77
	v_mul_f32_e32 v54, v54, v78
	v_mul_f32_e32 v55, v55, v79
	v_mul_f32_e32 v56, v56, v80
	v_mul_f32_e32 v57, v57, v81
	v_cvt_pk_bf16_f32 v216, v50, v51
	v_cvt_pk_bf16_f32 v217, v52, v53
	v_cvt_pk_bf16_f32 v218, v54, v55
	v_cvt_pk_bf16_f32 v219, v56, v57
	v_add_u32_e32 v67, 0x30000, v72
	global_store_dwordx4 v67, v[216:219], s[100:101] nt
	s_waitcnt lgkmcnt(0)
	v_mul_f32_e32 v58, v58, v74
	v_mul_f32_e32 v59, v59, v75
	v_mul_f32_e32 v60, v60, v76
	v_mul_f32_e32 v61, v61, v77
	v_mul_f32_e32 v62, v62, v78
	v_mul_f32_e32 v63, v63, v79
	v_mul_f32_e32 v64, v64, v80
	v_mul_f32_e32 v65, v65, v81
	v_cvt_pk_bf16_f32 v220, v58, v59
	v_cvt_pk_bf16_f32 v221, v60, v61
	v_cvt_pk_bf16_f32 v222, v62, v63
	v_cvt_pk_bf16_f32 v223, v64, v65
	v_add_u32_e32 v68, 0x38000, v72
	global_store_dwordx4 v68, v[220:223], s[100:101] nt
	s_branch .LBB0_339
; #define LAS __attribute__((address_space(3)))
; #define TR_LOAD(p) __builtin_nontemporal_load(p)
; __device__ __forceinline__ TrItem tr_decode(int it, const float* const* in, unsigned char* ws, int lane) {
;     ...
;     const int rh = r >> 3, rl = r & 7, nq = ndb >> DL, kbh = rh / nq, dbh = rh - kbh * nq;
;     const int kb = (kbh << KL) + (rl >> DL), db = (dbh << DL) + (rl & ((1 << DL) - 1)), d0 = db * 64, k0 = kb * 64;
;     ...
;     const int kb = r / ndb, db = r - kb * ndb, d0 = db * 64, k0 = kb * 64;
;     ...
;     const int blk = d0 + 32 * ((lane & 15) >> 3);
;     const float* src = W; int s0 = blk;
;     if (kind == 1) { const int pn = blk >> 8, bj = (blk >> 7) & 1, o = blk & 127; src = bj ? W2 : W; s0 = pn * 128 + o; }
;     else if (kind == 2) s0 = win_src(blk);
;     TrItem t; t.src = src + (size_t)(k0 + (lane >> 4)) * N + s0 + 4 * (lane & 7); t.gain = gain ? gain + k0 + 8 * (lane & 7) : nullptr;
;     t.dst = WT + (size_t)(d0 + (lane >> 3)) * K + k0 + 8 * (lane & 7); t.N = N; t.K = K; t.nts = nts && TR_NTS;
;     if (woh) { t.dst = WT + ((size_t)((k0 >> 9) * 2048 + d0 + (lane >> 3))) * 512 + (k0 & 511) + 8 * (lane & 7); t.K = 512; }
; __device__ __forceinline__ void tr_all(const float* const* in, unsigned char* ws, LAS float* scr, int gw, int ngw, int lane, const TrRanges rg) {
;     ...
;     for (int i = 0; i < 16; ++i) v[i] = TR_LOAD((const f32x4*)(cur.src + (size_t)(4 * i) * cur.N));
;     for (int it = gw; it < TR_CNT; it += ngw) {
;         const int nit = it + ngw; const bool hn = nit < TR_CNT;
;         TrItem nx = cur; f32x4 w[16];
;         if (hn) { nx = tr_decode(rg.item(nit), in, ws, lane);
; #pragma unroll
;             for (int i = 0; i < 16; ++i) w[i] = TR_LOAD((const f32x4*)(nx.src + (size_t)(4 * i) * nx.N)); }
;         LAS float* wp = scr + (lane >> 4) * 65 + 4 * (lane & 15);
; #pragma unroll
;         for (int i = 0; i < 16; ++i) { wp[(4 * i) * 65 + 0] = v[i][0]; wp[(4 * i) * 65 + 1] = v[i][1]; wp[(4 * i) * 65 + 2] = v[i][2]; wp[(4 * i) * 65 + 3] = v[i][3]; }
.Lseam_cv_0_1:
	s_cmp_gt_u32 s98, 7
	s_cbranch_scc1 .LBB0_339
	s_mov_b64 exec, -1
	s_lshl_b32 s99, s87, 1
	s_add_i32 s99, s99, s98
	s_add_i32 s99, s99, 0xfffffffa
	s_lshr_b32 s100, s99, 3
	s_lshr_b32 s101, s100, 3
	s_and_b32 s100, s100, 7
	s_and_b32 vcc_lo, s99, 7
	s_lshr_b32 vcc_hi, vcc_lo, 2
	s_lshl_b32 s101, s101, 1
	s_add_i32 s101, s101, vcc_hi
	s_and_b32 vcc_lo, vcc_lo, 3
	s_lshl_b32 s100, s100, 2
	s_add_i32 s100, s100, vcc_lo
	s_lshl_b32 s101, s101, 6
	s_lshl_b32 s100, s100, 6
	v_and_b32_e32 v66, 63, v1
	v_lshrrev_b32_e32 v67, 4, v66
	v_and_b32_e32 v68, 15, v66
	v_and_b32_e32 v73, 7, v66
	v_lshrrev_b32_e32 v72, 3, v66
	s_mul_i32 s99, s98, 0x4100
	v_mul_u32_u24_e32 v70, 0x104, v67
	v_lshl_add_u32 v70, v68, 4, v70
	v_add_u32_e32 v70, s99, v70
	v_mul_u32_u24_e32 v71, 0x820, v73
	v_lshl_add_u32 v71, v72, 2, v71
	v_add_u32_e32 v71, s99, v71
	s_lshl_b32 s99, s101, 13
	s_lshl_b32 vcc_lo, s100, 2
	s_add_i32 s99, s99, vcc_lo
	v_lshlrev_b32_e32 v69, 13, v67
	v_lshl_add_u32 v69, v68, 4, v69
	v_add_u32_e32 v69, s99, v69
	s_lshr_b32 s99, s101, 9
	s_lshl_b32 s99, s99, 21
	s_lshl_b32 vcc_lo, s100, 10
	s_add_i32 s99, s99, vcc_lo
	s_and_b32 vcc_lo, s101, 0x1ff
	s_lshl_b32 vcc_lo, vcc_lo, 1
	s_add_i32 s99, s99, vcc_lo
	v_lshlrev_b32_e32 v72, 10, v72
	v_lshl_add_u32 v72, v73, 4, v72
	v_add_u32_e32 v72, s99, v72
	v_readlane_b32 s100, v254, 32
	v_readlane_b32 s101, v254, 33
	s_nop 4
	global_load_dwordx4 v[2:5], v69, s[100:101] nt
	v_add_u32_e32 v68, 0x8000, v69
	global_load_dwordx4 v[6:9], v68, s[100:101] nt
	v_add_u32_e32 v67, 0x10000, v69
	global_load_dwordx4 v[10:13], v67, s[100:101] nt
	v_add_u32_e32 v68, 0x18000, v69
	global_load_dwordx4 v[14:17], v68, s[100:101] nt
	v_add_u32_e32 v67, 0x20000, v69
	global_load_dwordx4 v[18:21], v67, s[100:101] nt
	v_add_u32_e32 v68, 0x28000, v69
	global_load_dwordx4 v[22:25], v68, s[100:101] nt
	v_add_u32_e32 v67, 0x30000, v69
	global_load_dwordx4 v[26:29], v67, s[100:101] nt
	v_add_u32_e32 v68, 0x38000, v69
	global_load_dwordx4 v[30:33], v68, s[100:101] nt
	v_add_u32_e32 v67, 0x40000, v69
	global_load_dwordx4 v[34:37], v67, s[100:101] nt
	v_add_u32_e32 v68, 0x48000, v69
	global_load_dwordx4 v[38:41], v68, s[100:101] nt
	v_add_u32_e32 v67, 0x50000, v69
	global_load_dwordx4 v[42:45], v67, s[100:101] nt
	v_add_u32_e32 v68, 0x58000, v69
	global_load_dwordx4 v[46:49], v68, s[100:101] nt
	v_add_u32_e32 v67, 0x60000, v69
	global_load_dwordx4 v[50:53], v67, s[100:101] nt
	v_add_u32_e32 v68, 0x68000, v69
	global_load_dwordx4 v[54:57], v68, s[100:101] nt
	v_add_u32_e32 v67, 0x70000, v69
	global_load_dwordx4 v[58:61], v67, s[100:101] nt
	v_add_u32_e32 v68, 0x78000, v69
	global_load_dwordx4 v[62:65], v68, s[100:101] nt
	s_waitcnt vmcnt(15)
	ds_write_b32 v70, v2
	ds_write_b32 v70, v3 offset:4
	ds_write_b32 v70, v4 offset:8
	ds_write_b32 v70, v5 offset:12
	s_waitcnt vmcnt(14)
	ds_write_b32 v70, v6 offset:1040
	ds_write_b32 v70, v7 offset:1044
	ds_write_b32 v70, v8 offset:1048
	ds_write_b32 v70, v9 offset:1052
	s_waitcnt vmcnt(13)
	ds_write_b32 v70, v10 offset:2080
	ds_write_b32 v70, v11 offset:2084
	ds_write_b32 v70, v12 offset:2088
	ds_write_b32 v70, v13 offset:2092
	s_waitcnt vmcnt(12)
	ds_write_b32 v70, v14 offset:3120
	ds_write_b32 v70, v15 offset:3124
	ds_write_b32 v70, v16 offset:3128
	ds_write_b32 v70, v17 offset:3132
	s_waitcnt vmcnt(11)
	ds_write_b32 v70, v18 offset:4160
	ds_write_b32 v70, v19 offset:4164
	ds_write_b32 v70, v20 offset:4168
	ds_write_b32 v70, v21 offset:4172
	s_waitcnt vmcnt(10)
	ds_write_b32 v70, v22 offset:5200
	ds_write_b32 v70, v23 offset:5204
	ds_write_b32 v70, v24 offset:5208
	ds_write_b32 v70, v25 offset:5212
	s_waitcnt vmcnt(9)
	ds_write_b32 v70, v26 offset:6240
	ds_write_b32 v70, v27 offset:6244
	ds_write_b32 v70, v28 offset:6248
	ds_write_b32 v70, v29 offset:6252
	s_waitcnt vmcnt(8)
	ds_write_b32 v70, v30 offset:7280
	ds_write_b32 v70, v31 offset:7284
	ds_write_b32 v70, v32 offset:7288
	ds_write_b32 v70, v33 offset:7292
	s_waitcnt vmcnt(7)
	ds_write_b32 v70, v34 offset:8320
	ds_write_b32 v70, v35 offset:8324
	ds_write_b32 v70, v36 offset:8328
	ds_write_b32 v70, v37 offset:8332
	s_waitcnt vmcnt(6)
	ds_write_b32 v70, v38 offset:9360
	ds_write_b32 v70, v39 offset:9364
	ds_write_b32 v70, v40 offset:9368
	ds_write_b32 v70, v41 offset:9372
	s_waitcnt vmcnt(5)
	ds_write_b32 v70, v42 offset:10400
	ds_write_b32 v70, v43 offset:10404
	ds_write_b32 v70, v44 offset:10408
	ds_write_b32 v70, v45 offset:10412
	s_waitcnt vmcnt(4)
	ds_write_b32 v70, v46 offset:11440
	ds_write_b32 v70, v47 offset:11444
	ds_write_b32 v70, v48 offset:11448
	ds_write_b32 v70, v49 offset:11452
	s_waitcnt vmcnt(3)
; #define LAS __attribute__((address_space(3)))
; __device__ __forceinline__ unsigned cvtpk(float lo, float hi) { f32x2_t v = {lo, hi}; bf16x2_t b = __builtin_convertvector(v, bf16x2_t); return __builtin_bit_cast(unsigned, b); }
; __device__ __forceinline__ void tr_all(const float* const* in, unsigned char* ws, LAS float* scr, int gw, int ngw, int lane, const TrRanges rg) {
;     ...
;         const LAS float* rp = scr + (8 * (lane & 7)) * 65 + (lane >> 3);
; #pragma unroll
;         for (int j = 0; j < 8; ++j) { const LAS float* s = rp + 8 * j;
;             u32x4 o; o.x = cvtpk(s[0 * 65] * g0[0], s[1 * 65] * g0[1]); o.y = cvtpk(s[2 * 65] * g0[2], s[3 * 65] * g0[3]);
;             o.z = cvtpk(s[4 * 65] * g1[0], s[5 * 65] * g1[1]); o.w = cvtpk(s[6 * 65] * g1[2], s[7 * 65] * g1[3]);
;             if (cur.nts) __builtin_nontemporal_store(o, (u32x4*)(cur.dst + (size_t)(8 * j) * cur.K)); else *(u32x4*)(cur.dst + (size_t)(8 * j) * cur.K) = o; }
;         asm volatile("s_waitcnt lgkmcnt(0)" ::: "memory");
	ds_write_b32 v70, v50 offset:12480
	ds_write_b32 v70, v51 offset:12484
	ds_write_b32 v70, v52 offset:12488
	ds_write_b32 v70, v53 offset:12492
	s_waitcnt vmcnt(2)
	ds_write_b32 v70, v54 offset:13520
	ds_write_b32 v70, v55 offset:13524
	ds_write_b32 v70, v56 offset:13528
	ds_write_b32 v70, v57 offset:13532
	s_waitcnt vmcnt(1)
	ds_write_b32 v70, v58 offset:14560
	ds_write_b32 v70, v59 offset:14564
	ds_write_b32 v70, v60 offset:14568
	ds_write_b32 v70, v61 offset:14572
	s_waitcnt vmcnt(0)
	ds_write_b32 v70, v62 offset:15600
	ds_write_b32 v70, v63 offset:15604
	ds_write_b32 v70, v64 offset:15608
	ds_write_b32 v70, v65 offset:15612
	s_add_u32 s100, s84, 0x8700000
	s_addc_u32 s101, s85, 0
	s_waitcnt lgkmcnt(0)
	ds_read_b32 v2, v71
	ds_read_b32 v3, v71 offset:260
	ds_read_b32 v4, v71 offset:520
	ds_read_b32 v5, v71 offset:780
	ds_read_b32 v6, v71 offset:1040
	ds_read_b32 v7, v71 offset:1300
	ds_read_b32 v8, v71 offset:1560
	ds_read_b32 v9, v71 offset:1820
	ds_read_b32 v10, v71 offset:32
	ds_read_b32 v11, v71 offset:292
	ds_read_b32 v12, v71 offset:552
	ds_read_b32 v13, v71 offset:812
	ds_read_b32 v14, v71 offset:1072
	ds_read_b32 v15, v71 offset:1332
	ds_read_b32 v16, v71 offset:1592
	ds_read_b32 v17, v71 offset:1852
	ds_read_b32 v18, v71 offset:64
	ds_read_b32 v19, v71 offset:324
	ds_read_b32 v20, v71 offset:584
	ds_read_b32 v21, v71 offset:844
	ds_read_b32 v22, v71 offset:1104
	ds_read_b32 v23, v71 offset:1364
	ds_read_b32 v24, v71 offset:1624
	ds_read_b32 v25, v71 offset:1884
	ds_read_b32 v26, v71 offset:96
	ds_read_b32 v27, v71 offset:356
	ds_read_b32 v28, v71 offset:616
	ds_read_b32 v29, v71 offset:876
	ds_read_b32 v30, v71 offset:1136
	ds_read_b32 v31, v71 offset:1396
	ds_read_b32 v32, v71 offset:1656
	ds_read_b32 v33, v71 offset:1916
	ds_read_b32 v34, v71 offset:128
	ds_read_b32 v35, v71 offset:388
	ds_read_b32 v36, v71 offset:648
	ds_read_b32 v37, v71 offset:908
	ds_read_b32 v38, v71 offset:1168
	ds_read_b32 v39, v71 offset:1428
	ds_read_b32 v40, v71 offset:1688
	ds_read_b32 v41, v71 offset:1948
	ds_read_b32 v42, v71 offset:160
	ds_read_b32 v43, v71 offset:420
	ds_read_b32 v44, v71 offset:680
	ds_read_b32 v45, v71 offset:940
	ds_read_b32 v46, v71 offset:1200
	ds_read_b32 v47, v71 offset:1460
	ds_read_b32 v48, v71 offset:1720
	ds_read_b32 v49, v71 offset:1980
	ds_read_b32 v50, v71 offset:192
	ds_read_b32 v51, v71 offset:452
	ds_read_b32 v52, v71 offset:712
	ds_read_b32 v53, v71 offset:972
	ds_read_b32 v54, v71 offset:1232
	ds_read_b32 v55, v71 offset:1492
	ds_read_b32 v56, v71 offset:1752
	ds_read_b32 v57, v71 offset:2012
	ds_read_b32 v58, v71 offset:224
	ds_read_b32 v59, v71 offset:484
	ds_read_b32 v60, v71 offset:744
	ds_read_b32 v61, v71 offset:1004
	ds_read_b32 v62, v71 offset:1264
	ds_read_b32 v63, v71 offset:1524
	ds_read_b32 v64, v71 offset:1784
	ds_read_b32 v65, v71 offset:2044
	s_waitcnt lgkmcnt(15)
	v_cvt_pk_bf16_f32 v192, v2, v3
	v_cvt_pk_bf16_f32 v193, v4, v5
	v_cvt_pk_bf16_f32 v194, v6, v7
	v_cvt_pk_bf16_f32 v195, v8, v9
	global_store_dwordx4 v72, v[192:195], s[100:101] nt
	s_waitcnt lgkmcnt(15)
	v_cvt_pk_bf16_f32 v196, v10, v11
	v_cvt_pk_bf16_f32 v197, v12, v13
	v_cvt_pk_bf16_f32 v198, v14, v15
	v_cvt_pk_bf16_f32 v199, v16, v17
	v_add_u32_e32 v68, 0x2000, v72
	global_store_dwordx4 v68, v[196:199], s[100:101] nt
	s_waitcnt lgkmcnt(15)
	v_cvt_pk_bf16_f32 v200, v18, v19
	v_cvt_pk_bf16_f32 v201, v20, v21
	v_cvt_pk_bf16_f32 v202, v22, v23
	v_cvt_pk_bf16_f32 v203, v24, v25
	v_add_u32_e32 v67, 0x4000, v72
	global_store_dwordx4 v67, v[200:203], s[100:101] nt
	s_waitcnt lgkmcnt(15)
	v_cvt_pk_bf16_f32 v204, v26, v27
	v_cvt_pk_bf16_f32 v205, v28, v29
	v_cvt_pk_bf16_f32 v206, v30, v31
	v_cvt_pk_bf16_f32 v207, v32, v33
	v_add_u32_e32 v68, 0x6000, v72
	global_store_dwordx4 v68, v[204:207], s[100:101] nt
	s_waitcnt lgkmcnt(15)
	v_cvt_pk_bf16_f32 v208, v34, v35
	v_cvt_pk_bf16_f32 v209, v36, v37
	v_cvt_pk_bf16_f32 v210, v38, v39
	v_cvt_pk_bf16_f32 v211, v40, v41
	v_add_u32_e32 v67, 0x8000, v72
	global_store_dwordx4 v67, v[208:211], s[100:101] nt
	s_waitcnt lgkmcnt(15)
	v_cvt_pk_bf16_f32 v212, v42, v43
	v_cvt_pk_bf16_f32 v213, v44, v45
	v_cvt_pk_bf16_f32 v214, v46, v47
	v_cvt_pk_bf16_f32 v215, v48, v49
	v_add_u32_e32 v68, 0xa000, v72
	global_store_dwordx4 v68, v[212:215], s[100:101] nt
	s_waitcnt lgkmcnt(8)
	v_cvt_pk_bf16_f32 v216, v50, v51
	v_cvt_pk_bf16_f32 v217, v52, v53
	v_cvt_pk_bf16_f32 v218, v54, v55
	v_cvt_pk_bf16_f32 v219, v56, v57
	v_add_u32_e32 v67, 0xc000, v72
	global_store_dwordx4 v67, v[216:219], s[100:101] nt
	s_waitcnt lgkmcnt(0)
	v_cvt_pk_bf16_f32 v220, v58, v59
	v_cvt_pk_bf16_f32 v221, v60, v61
	v_cvt_pk_bf16_f32 v222, v62, v63
	v_cvt_pk_bf16_f32 v223, v64, v65
	v_add_u32_e32 v68, 0xe000, v72
	global_store_dwordx4 v68, v[220:223], s[100:101] nt

; #define LAS __attribute__((address_space(3)))
; #define TR_LOAD(p) __builtin_nontemporal_load(p)
; __device__ __forceinline__ TrItem tr_decode(int it, const float* const* in, unsigned char* ws, int lane) {
;     ...
;     const int rh = r >> 3, rl = r & 7, nq = ndb >> DL, kbh = rh / nq, dbh = rh - kbh * nq;
;     const int kb = (kbh << KL) + (rl >> DL), db = (dbh << DL) + (rl & ((1 << DL) - 1)), d0 = db * 64, k0 = kb * 64;
;     ...
;     const int kb = r / ndb, db = r - kb * ndb, d0 = db * 64, k0 = kb * 64;
;     ...
;     const int blk = d0 + 32 * ((lane & 15) >> 3);
;     const float* src = W; int s0 = blk;
;     if (kind == 1) { const int pn = blk >> 8, bj = (blk >> 7) & 1, o = blk & 127; src = bj ? W2 : W; s0 = pn * 128 + o; }
;     else if (kind == 2) s0 = win_src(blk);
;     TrItem t; t.src = src + (size_t)(k0 + (lane >> 4)) * N + s0 + 4 * (lane & 7); t.gain = gain ? gain + k0 + 8 * (lane & 7) : nullptr;
;     t.dst = WT + (size_t)(d0 + (lane >> 3)) * K + k0 + 8 * (lane & 7); t.N = N; t.K = K; t.nts = nts && TR_NTS;
; __device__ __forceinline__ void tr_all(const float* const* in, unsigned char* ws, LAS float* scr, int gw, int ngw, int lane, const TrRanges rg) {
;     ...
;     for (int i = 0; i < 16; ++i) v[i] = TR_LOAD((const f32x4*)(cur.src + (size_t)(4 * i) * cur.N));
;     for (int it = gw; it < TR_CNT; it += ngw) {
;         const int nit = it + ngw; const bool hn = nit < TR_CNT;
;         TrItem nx = cur; f32x4 w[16];
;         if (hn) { nx = tr_decode(rg.item(nit), in, ws, lane);
; #pragma unroll
;             for (int i = 0; i < 16; ++i) w[i] = TR_LOAD((const f32x4*)(nx.src + (size_t)(4 * i) * nx.N)); }
;         LAS float* wp = scr + (lane >> 4) * 65 + 4 * (lane & 15);
; #pragma unroll
;         for (int i = 0; i < 16; ++i) { wp[(4 * i) * 65 + 0] = v[i][0]; wp[(4 * i) * 65 + 1] = v[i][1]; wp[(4 * i) * 65 + 2] = v[i][2]; wp[(4 * i) * 65 + 3] = v[i][3]; }
;         f32x4 g0 = {1.f, 1.f, 1.f, 1.f}, g1 = {1.f, 1.f, 1.f, 1.f};
;         if (cur.gain) { g0 = *(const f32x4*)cur.gain; g1 = *(const f32x4*)(cur.gain + 4); }
.Lseam_cv_1:
	s_cmp_lt_u32 s98, 2
	s_cbranch_scc1 .LBB0_570
	s_cmp_gt_u32 s98, 5
	s_cbranch_scc1 .Lseam_cv_1_1
	s_mov_b64 exec, -1
	s_lshl_b32 s99, s87, 2
	s_add_i32 s99, s99, s98
	s_add_i32 s99, s99, 0x9fe
	s_lshr_b32 s100, s99, 3
	s_mul_i32 s101, s100, 0x5d2
	s_lshr_b32 s101, s101, 16
	s_mul_i32 vcc_lo, s101, 44
	s_sub_i32 s100, s100, vcc_lo
	s_and_b32 vcc_lo, s99, 7
	s_lshr_b32 vcc_hi, vcc_lo, 2
	s_lshl_b32 s101, s101, 1
	s_add_i32 s101, s101, vcc_hi
	s_and_b32 vcc_lo, vcc_lo, 3
	s_lshl_b32 s100, s100, 2
	s_add_i32 s100, s100, vcc_lo
	s_lshl_b32 s101, s101, 6
	s_lshl_b32 s100, s100, 6
	v_and_b32_e32 v66, 63, v1
	v_lshrrev_b32_e32 v67, 4, v66
	v_and_b32_e32 v68, 15, v66
	v_and_b32_e32 v73, 7, v66
	v_lshrrev_b32_e32 v72, 3, v66
	s_mul_i32 s99, s98, 0x4100
	v_mul_u32_u24_e32 v70, 0x104, v67
	v_lshl_add_u32 v70, v68, 4, v70
	v_add_u32_e32 v70, s99, v70
	v_mul_u32_u24_e32 v71, 0x820, v73
	v_lshl_add_u32 v71, v72, 2, v71
	v_add_u32_e32 v71, s99, v71
	s_mul_i32 s99, s101, 0x1600
	s_lshr_b32 vcc_lo, s100, 8
	s_lshl_b32 vcc_lo, vcc_lo, 7
	s_add_i32 s99, s99, vcc_lo
	s_and_b32 vcc_lo, s100, 0x7f
	s_add_i32 s99, s99, vcc_lo
	s_lshl_b32 s99, s99, 2
	v_mul_u32_u24_e32 v69, 0x5800, v67
	v_lshl_add_u32 v69, v68, 4, v69
	v_add_u32_e32 v69, s99, v69
	s_lshl_b32 s99, s100, 12
	s_lshl_b32 vcc_lo, s101, 1
	s_add_i32 s99, s99, vcc_lo
	v_lshlrev_b32_e32 v72, 12, v72
	v_lshl_add_u32 v72, v73, 4, v72
	v_add_u32_e32 v72, s99, v72
	s_lshl_b32 s99, s101, 2
	v_lshlrev_b32_e32 v73, 5, v73
	v_add_u32_e32 v73, s99, v73
	s_nop 0
	s_bitcmp1_b32 s100, 7
	v_readlane_b32 s100, v254, 6
	v_readlane_b32 s101, v254, 7
	v_readlane_b32 s98, v254, 8
	v_readlane_b32 s99, v254, 9
	s_nop 3
	s_cselect_b32 s100, s98, s100
	s_cselect_b32 s101, s99, s101
	v_readlane_b32 s98, v254, 4
	v_readlane_b32 s99, v254, 5
	global_load_dwordx4 v[2:5], v69, s[100:101] nt
	v_add_u32_e32 v68, 0x16000, v69
	global_load_dwordx4 v[6:9], v68, s[100:101] nt
	v_add_u32_e32 v67, 0x2c000, v69
	global_load_dwordx4 v[10:13], v67, s[100:101] nt
	v_add_u32_e32 v68, 0x42000, v69
	global_load_dwordx4 v[14:17], v68, s[100:101] nt
	v_add_u32_e32 v67, 0x58000, v69
	global_load_dwordx4 v[18:21], v67, s[100:101] nt
	v_add_u32_e32 v68, 0x6e000, v69
	global_load_dwordx4 v[22:25], v68, s[100:101] nt
	v_add_u32_e32 v67, 0x84000, v69
	global_load_dwordx4 v[26:29], v67, s[100:101] nt
	v_add_u32_e32 v68, 0x9a000, v69
	global_load_dwordx4 v[30:33], v68, s[100:101] nt
	v_add_u32_e32 v67, 0xb0000, v69
	global_load_dwordx4 v[34:37], v67, s[100:101] nt
	v_add_u32_e32 v68, 0xc6000, v69
	global_load_dwordx4 v[38:41], v68, s[100:101] nt
	v_add_u32_e32 v67, 0xdc000, v69
	global_load_dwordx4 v[42:45], v67, s[100:101] nt
	v_add_u32_e32 v68, 0xf2000, v69
	global_load_dwordx4 v[46:49], v68, s[100:101] nt
	v_add_u32_e32 v67, 0x108000, v69
	global_load_dwordx4 v[50:53], v67, s[100:101] nt
	v_add_u32_e32 v68, 0x11e000, v69
	global_load_dwordx4 v[54:57], v68, s[100:101] nt
	v_add_u32_e32 v67, 0x134000, v69
	global_load_dwordx4 v[58:61], v67, s[100:101] nt
	v_add_u32_e32 v68, 0x14a000, v69
	global_load_dwordx4 v[62:65], v68, s[100:101] nt
	global_load_dwordx4 v[74:77], v73, s[98:99]
	global_load_dwordx4 v[78:81], v73, s[98:99] offset:16
	s_waitcnt vmcnt(17)
	ds_write_b32 v70, v2
	ds_write_b32 v70, v3 offset:4
	ds_write_b32 v70, v4 offset:8
	ds_write_b32 v70, v5 offset:12
	s_waitcnt vmcnt(16)
	ds_write_b32 v70, v6 offset:1040
	ds_write_b32 v70, v7 offset:1044
	ds_write_b32 v70, v8 offset:1048
	ds_write_b32 v70, v9 offset:1052
	s_waitcnt vmcnt(15)
	ds_write_b32 v70, v10 offset:2080
	ds_write_b32 v70, v11 offset:2084
	ds_write_b32 v70, v12 offset:2088
	ds_write_b32 v70, v13 offset:2092
	s_waitcnt vmcnt(14)
	ds_write_b32 v70, v14 offset:3120
	ds_write_b32 v70, v15 offset:3124
	ds_write_b32 v70, v16 offset:3128
	ds_write_b32 v70, v17 offset:3132
	s_waitcnt vmcnt(13)
	ds_write_b32 v70, v18 offset:4160
	ds_write_b32 v70, v19 offset:4164
	ds_write_b32 v70, v20 offset:4168
	ds_write_b32 v70, v21 offset:4172
	s_waitcnt vmcnt(12)
	ds_write_b32 v70, v22 offset:5200
	ds_write_b32 v70, v23 offset:5204
	ds_write_b32 v70, v24 offset:5208
	ds_write_b32 v70, v25 offset:5212
	s_waitcnt vmcnt(11)
	ds_write_b32 v70, v26 offset:6240
	ds_write_b32 v70, v27 offset:6244
	ds_write_b32 v70, v28 offset:6248
	ds_write_b32 v70, v29 offset:6252
	s_waitcnt vmcnt(10)
	ds_write_b32 v70, v30 offset:7280
	ds_write_b32 v70, v31 offset:7284
	ds_write_b32 v70, v32 offset:7288
	ds_write_b32 v70, v33 offset:7292
	s_waitcnt vmcnt(9)
	ds_write_b32 v70, v34 offset:8320
	ds_write_b32 v70, v35 offset:8324
	ds_write_b32 v70, v36 offset:8328
	ds_write_b32 v70, v37 offset:8332
	s_waitcnt vmcnt(8)
	ds_write_b32 v70, v38 offset:9360
	ds_write_b32 v70, v39 offset:9364
	ds_write_b32 v70, v40 offset:9368
	ds_write_b32 v70, v41 offset:9372
	s_waitcnt vmcnt(7)
	ds_write_b32 v70, v42 offset:10400
	ds_write_b32 v70, v43 offset:10404
	ds_write_b32 v70, v44 offset:10408
	ds_write_b32 v70, v45 offset:10412
	s_waitcnt vmcnt(6)
	ds_write_b32 v70, v46 offset:11440
	ds_write_b32 v70, v47 offset:11444
	ds_write_b32 v70, v48 offset:11448
	ds_write_b32 v70, v49 offset:11452
	s_waitcnt vmcnt(5)
	ds_write_b32 v70, v50 offset:12480
	ds_write_b32 v70, v51 offset:12484
	ds_write_b32 v70, v52 offset:12488
	ds_write_b32 v70, v53 offset:12492
	s_waitcnt vmcnt(4)
	ds_write_b32 v70, v54 offset:13520
	ds_write_b32 v70, v55 offset:13524
	ds_write_b32 v70, v56 offset:13528
	ds_write_b32 v70, v57 offset:13532
	s_waitcnt vmcnt(3)
	ds_write_b32 v70, v58 offset:14560
	ds_write_b32 v70, v59 offset:14564
	ds_write_b32 v70, v60 offset:14568
	ds_write_b32 v70, v61 offset:14572
	s_waitcnt vmcnt(2)
; #define LAS __attribute__((address_space(3)))
; __device__ __forceinline__ unsigned cvtpk(float lo, float hi) { f32x2_t v = {lo, hi}; bf16x2_t b = __builtin_convertvector(v, bf16x2_t); return __builtin_bit_cast(unsigned, b); }
; __device__ __forceinline__ void tr_all(const float* const* in, unsigned char* ws, LAS float* scr, int gw, int ngw, int lane, const TrRanges rg) {
;     ...
;         const LAS float* rp = scr + (8 * (lane & 7)) * 65 + (lane >> 3);
; #pragma unroll
;         for (int j = 0; j < 8; ++j) { const LAS float* s = rp + 8 * j;
;             u32x4 o; o.x = cvtpk(s[0 * 65] * g0[0], s[1 * 65] * g0[1]); o.y = cvtpk(s[2 * 65] * g0[2], s[3 * 65] * g0[3]);
;             o.z = cvtpk(s[4 * 65] * g1[0], s[5 * 65] * g1[1]); o.w = cvtpk(s[6 * 65] * g1[2], s[7 * 65] * g1[3]);
;             if (cur.nts) __builtin_nontemporal_store(o, (u32x4*)(cur.dst + (size_t)(8 * j) * cur.K)); else *(u32x4*)(cur.dst + (size_t)(8 * j) * cur.K) = o; }
;         asm volatile("s_waitcnt lgkmcnt(0)" ::: "memory");
	ds_write_b32 v70, v62 offset:15600
	ds_write_b32 v70, v63 offset:15604
	ds_write_b32 v70, v64 offset:15608
	ds_write_b32 v70, v65 offset:15612
	s_add_u32 s100, s84, 0x8f00000
	s_addc_u32 s101, s85, 0
	s_waitcnt vmcnt(0) lgkmcnt(0)
	ds_read_b32 v2, v71
	ds_read_b32 v3, v71 offset:260
	ds_read_b32 v4, v71 offset:520
	ds_read_b32 v5, v71 offset:780
	ds_read_b32 v6, v71 offset:1040
	ds_read_b32 v7, v71 offset:1300
	ds_read_b32 v8, v71 offset:1560
	ds_read_b32 v9, v71 offset:1820
	ds_read_b32 v10, v71 offset:32
	ds_read_b32 v11, v71 offset:292
	ds_read_b32 v12, v71 offset:552
	ds_read_b32 v13, v71 offset:812
	ds_read_b32 v14, v71 offset:1072
	ds_read_b32 v15, v71 offset:1332
	ds_read_b32 v16, v71 offset:1592
	ds_read_b32 v17, v71 offset:1852
	ds_read_b32 v18, v71 offset:64
	ds_read_b32 v19, v71 offset:324
	ds_read_b32 v20, v71 offset:584
	ds_read_b32 v21, v71 offset:844
	ds_read_b32 v22, v71 offset:1104
	ds_read_b32 v23, v71 offset:1364
	ds_read_b32 v24, v71 offset:1624
	ds_read_b32 v25, v71 offset:1884
	ds_read_b32 v26, v71 offset:96
	ds_read_b32 v27, v71 offset:356
	ds_read_b32 v28, v71 offset:616
	ds_read_b32 v29, v71 offset:876
	ds_read_b32 v30, v71 offset:1136
	ds_read_b32 v31, v71 offset:1396
	ds_read_b32 v32, v71 offset:1656
	ds_read_b32 v33, v71 offset:1916
	ds_read_b32 v34, v71 offset:128
	ds_read_b32 v35, v71 offset:388
	ds_read_b32 v36, v71 offset:648
	ds_read_b32 v37, v71 offset:908
	ds_read_b32 v38, v71 offset:1168
	ds_read_b32 v39, v71 offset:1428
	ds_read_b32 v40, v71 offset:1688
	ds_read_b32 v41, v71 offset:1948
	ds_read_b32 v42, v71 offset:160
	ds_read_b32 v43, v71 offset:420
	ds_read_b32 v44, v71 offset:680
	ds_read_b32 v45, v71 offset:940
	ds_read_b32 v46, v71 offset:1200
	ds_read_b32 v47, v71 offset:1460
	ds_read_b32 v48, v71 offset:1720
	ds_read_b32 v49, v71 offset:1980
	ds_read_b32 v50, v71 offset:192
	ds_read_b32 v51, v71 offset:452
	ds_read_b32 v52, v71 offset:712
	ds_read_b32 v53, v71 offset:972
	ds_read_b32 v54, v71 offset:1232
	ds_read_b32 v55, v71 offset:1492
	ds_read_b32 v56, v71 offset:1752
	ds_read_b32 v57, v71 offset:2012
	ds_read_b32 v58, v71 offset:224
	ds_read_b32 v59, v71 offset:484
	ds_read_b32 v60, v71 offset:744
	ds_read_b32 v61, v71 offset:1004
	ds_read_b32 v62, v71 offset:1264
	ds_read_b32 v63, v71 offset:1524
	ds_read_b32 v64, v71 offset:1784
	ds_read_b32 v65, v71 offset:2044
	s_waitcnt lgkmcnt(15)
	v_mul_f32_e32 v2, v2, v74
	v_mul_f32_e32 v3, v3, v75
	v_mul_f32_e32 v4, v4, v76
	v_mul_f32_e32 v5, v5, v77
	v_mul_f32_e32 v6, v6, v78
	v_mul_f32_e32 v7, v7, v79
	v_mul_f32_e32 v8, v8, v80
	v_mul_f32_e32 v9, v9, v81
	v_cvt_pk_bf16_f32 v192, v2, v3
	v_cvt_pk_bf16_f32 v193, v4, v5
	v_cvt_pk_bf16_f32 v194, v6, v7
	v_cvt_pk_bf16_f32 v195, v8, v9
	global_store_dwordx4 v72, v[192:195], s[100:101] nt
	s_waitcnt lgkmcnt(15)
	v_mul_f32_e32 v10, v10, v74
	v_mul_f32_e32 v11, v11, v75
	v_mul_f32_e32 v12, v12, v76
	v_mul_f32_e32 v13, v13, v77
	v_mul_f32_e32 v14, v14, v78
	v_mul_f32_e32 v15, v15, v79
	v_mul_f32_e32 v16, v16, v80
	v_mul_f32_e32 v17, v17, v81
	v_cvt_pk_bf16_f32 v196, v10, v11
	v_cvt_pk_bf16_f32 v197, v12, v13
	v_cvt_pk_bf16_f32 v198, v14, v15
	v_cvt_pk_bf16_f32 v199, v16, v17
	v_add_u32_e32 v68, 0x8000, v72
	global_store_dwordx4 v68, v[196:199], s[100:101] nt
	s_waitcnt lgkmcnt(15)
	v_mul_f32_e32 v18, v18, v74
	v_mul_f32_e32 v19, v19, v75
	v_mul_f32_e32 v20, v20, v76
	v_mul_f32_e32 v21, v21, v77
	v_mul_f32_e32 v22, v22, v78
	v_mul_f32_e32 v23, v23, v79
	v_mul_f32_e32 v24, v24, v80
	v_mul_f32_e32 v25, v25, v81
	v_cvt_pk_bf16_f32 v200, v18, v19
	v_cvt_pk_bf16_f32 v201, v20, v21
	v_cvt_pk_bf16_f32 v202, v22, v23
	v_cvt_pk_bf16_f32 v203, v24, v25
	v_add_u32_e32 v67, 0x10000, v72
	global_store_dwordx4 v67, v[200:203], s[100:101] nt
	s_waitcnt lgkmcnt(15)
	v_mul_f32_e32 v26, v26, v74
	v_mul_f32_e32 v27, v27, v75
	v_mul_f32_e32 v28, v28, v76
	v_mul_f32_e32 v29, v29, v77
	v_mul_f32_e32 v30, v30, v78
	v_mul_f32_e32 v31, v31, v79
	v_mul_f32_e32 v32, v32, v80
	v_mul_f32_e32 v33, v33, v81
	v_cvt_pk_bf16_f32 v204, v26, v27
	v_cvt_pk_bf16_f32 v205, v28, v29
	v_cvt_pk_bf16_f32 v206, v30, v31
	v_cvt_pk_bf16_f32 v207, v32, v33
	v_add_u32_e32 v68, 0x18000, v72
	global_store_dwordx4 v68, v[204:207], s[100:101] nt
	s_waitcnt lgkmcnt(15)
	v_mul_f32_e32 v34, v34, v74
	v_mul_f32_e32 v35, v35, v75
	v_mul_f32_e32 v36, v36, v76
	v_mul_f32_e32 v37, v37, v77
	v_mul_f32_e32 v38, v38, v78
	v_mul_f32_e32 v39, v39, v79
	v_mul_f32_e32 v40, v40, v80
	v_mul_f32_e32 v41, v41, v81
	v_cvt_pk_bf16_f32 v208, v34, v35
	v_cvt_pk_bf16_f32 v209, v36, v37
	v_cvt_pk_bf16_f32 v210, v38, v39
	v_cvt_pk_bf16_f32 v211, v40, v41
	v_add_u32_e32 v67, 0x20000, v72
	global_store_dwordx4 v67, v[208:211], s[100:101] nt
	s_waitcnt lgkmcnt(15)
	v_mul_f32_e32 v42, v42, v74
	v_mul_f32_e32 v43, v43, v75
	v_mul_f32_e32 v44, v44, v76
	v_mul_f32_e32 v45, v45, v77
	v_mul_f32_e32 v46, v46, v78
	v_mul_f32_e32 v47, v47, v79
	v_mul_f32_e32 v48, v48, v80
	v_mul_f32_e32 v49, v49, v81
	v_cvt_pk_bf16_f32 v212, v42, v43
	v_cvt_pk_bf16_f32 v213, v44, v45
	v_cvt_pk_bf16_f32 v214, v46, v47
	v_cvt_pk_bf16_f32 v215, v48, v49
	v_add_u32_e32 v68, 0x28000, v72
	global_store_dwordx4 v68, v[212:215], s[100:101] nt
	s_waitcnt lgkmcnt(8)
	v_mul_f32_e32 v50, v50, v74
	v_mul_f32_e32 v51, v51, v75
	v_mul_f32_e32 v52, v52, v76
	v_mul_f32_e32 v53, v53, v77
	v_mul_f32_e32 v54, v54, v78
	v_mul_f32_e32 v55, v55, v79
	v_mul_f32_e32 v56, v56, v80
	v_mul_f32_e32 v57, v57, v81
	v_cvt_pk_bf16_f32 v216, v50, v51
	v_cvt_pk_bf16_f32 v217, v52, v53
	v_cvt_pk_bf16_f32 v218, v54, v55
	v_cvt_pk_bf16_f32 v219, v56, v57
	v_add_u32_e32 v67, 0x30000, v72
	global_store_dwordx4 v67, v[216:219], s[100:101] nt
	s_waitcnt lgkmcnt(0)
	v_mul_f32_e32 v58, v58, v74
	v_mul_f32_e32 v59, v59, v75
	v_mul_f32_e32 v60, v60, v76
	v_mul_f32_e32 v61, v61, v77
	v_mul_f32_e32 v62, v62, v78
	v_mul_f32_e32 v63, v63, v79
	v_mul_f32_e32 v64, v64, v80
	v_mul_f32_e32 v65, v65, v81
	v_cvt_pk_bf16_f32 v220, v58, v59
	v_cvt_pk_bf16_f32 v221, v60, v61
	v_cvt_pk_bf16_f32 v222, v62, v63
	v_cvt_pk_bf16_f32 v223, v64, v65
	v_add_u32_e32 v68, 0x38000, v72
	global_store_dwordx4 v68, v[220:223], s[100:101] nt
	s_branch .LBB0_570
; #define LAS __attribute__((address_space(3)))
; #define TR_LOAD(p) __builtin_nontemporal_load(p)
; __device__ __forceinline__ TrItem tr_decode(int it, const float* const* in, unsigned char* ws, int lane) {
;     ...
;     const int rh = r >> 3, rl = r & 7, nq = ndb >> DL, kbh = rh / nq, dbh = rh - kbh * nq;
;     const int kb = (kbh << KL) + (rl >> DL), db = (dbh << DL) + (rl & ((1 << DL) - 1)), d0 = db * 64, k0 = kb * 64;
;     ...
;     const int kb = r / ndb, db = r - kb * ndb, d0 = db * 64, k0 = kb * 64;
;     ...
;     const int blk = d0 + 32 * ((lane & 15) >> 3);
;     const float* src = W; int s0 = blk;
;     if (kind == 1) { const int pn = blk >> 8, bj = (blk >> 7) & 1, o = blk & 127; src = bj ? W2 : W; s0 = pn * 128 + o; }
;     else if (kind == 2) s0 = win_src(blk);
;     TrItem t; t.src = src + (size_t)(k0 + (lane >> 4)) * N + s0 + 4 * (lane & 7); t.gain = gain ? gain + k0 + 8 * (lane & 7) : nullptr;
;     t.dst = WT + (size_t)(d0 + (lane >> 3)) * K + k0 + 8 * (lane & 7); t.N = N; t.K = K; t.nts = nts && TR_NTS;
;     if (woh) { t.dst = WT + ((size_t)((k0 >> 9) * 2048 + d0 + (lane >> 3))) * 512 + (k0 & 511) + 8 * (lane & 7); t.K = 512; }
; __device__ __forceinline__ void tr_all(const float* const* in, unsigned char* ws, LAS float* scr, int gw, int ngw, int lane, const TrRanges rg) {
;     ...
;     for (int i = 0; i < 16; ++i) v[i] = TR_LOAD((const f32x4*)(cur.src + (size_t)(4 * i) * cur.N));
;     for (int it = gw; it < TR_CNT; it += ngw) {
;         const int nit = it + ngw; const bool hn = nit < TR_CNT;
;         TrItem nx = cur; f32x4 w[16];
;         if (hn) { nx = tr_decode(rg.item(nit), in, ws, lane);
; #pragma unroll
;             for (int i = 0; i < 16; ++i) w[i] = TR_LOAD((const f32x4*)(nx.src + (size_t)(4 * i) * nx.N)); }
;         LAS float* wp = scr + (lane >> 4) * 65 + 4 * (lane & 15);
; #pragma unroll
;         for (int i = 0; i < 16; ++i) { wp[(4 * i) * 65 + 0] = v[i][0]; wp[(4 * i) * 65 + 1] = v[i][1]; wp[(4 * i) * 65 + 2] = v[i][2]; wp[(4 * i) * 65 + 3] = v[i][3]; }
.Lseam_cv_1_1:
	s_cmp_gt_u32 s98, 7
	s_cbranch_scc1 .LBB0_570
	s_mov_b64 exec, -1
	s_lshl_b32 s99, s87, 1
	s_add_i32 s99, s99, s98
	s_add_i32 s99, s99, 0x1fa
	s_lshr_b32 s100, s99, 3
	s_lshr_b32 s101, s100, 3
	s_and_b32 s100, s100, 7
	s_and_b32 vcc_lo, s99, 7
	s_lshr_b32 vcc_hi, vcc_lo, 2
	s_lshl_b32 s101, s101, 1
	s_add_i32 s101, s101, vcc_hi
	s_and_b32 vcc_lo, vcc_lo, 3
	s_lshl_b32 s100, s100, 2
	s_add_i32 s100, s100, vcc_lo
	s_lshl_b32 s101, s101, 6
	s_lshl_b32 s100, s100, 6
	v_and_b32_e32 v66, 63, v1
	v_lshrrev_b32_e32 v67, 4, v66
	v_and_b32_e32 v68, 15, v66
	v_and_b32_e32 v73, 7, v66
	v_lshrrev_b32_e32 v72, 3, v66
	s_mul_i32 s99, s98, 0x4100
	v_mul_u32_u24_e32 v70, 0x104, v67
	v_lshl_add_u32 v70, v68, 4, v70
	v_add_u32_e32 v70, s99, v70
	v_mul_u32_u24_e32 v71, 0x820, v73
	v_lshl_add_u32 v71, v72, 2, v71
	v_add_u32_e32 v71, s99, v71
	s_lshl_b32 s99, s101, 13
	s_lshl_b32 vcc_lo, s100, 2
	s_add_i32 s99, s99, vcc_lo
	v_lshlrev_b32_e32 v69, 13, v67
	v_lshl_add_u32 v69, v68, 4, v69
	v_add_u32_e32 v69, s99, v69
	s_lshr_b32 s99, s101, 9
	s_lshl_b32 s99, s99, 21
	s_lshl_b32 vcc_lo, s100, 10
	s_add_i32 s99, s99, vcc_lo
	s_and_b32 vcc_lo, s101, 0x1ff
	s_lshl_b32 vcc_lo, vcc_lo, 1
	s_add_i32 s99, s99, vcc_lo
	v_lshlrev_b32_e32 v72, 10, v72
	v_lshl_add_u32 v72, v73, 4, v72
	v_add_u32_e32 v72, s99, v72
	v_readlane_b32 s100, v254, 32
	v_readlane_b32 s101, v254, 33
	s_nop 4
	global_load_dwordx4 v[2:5], v69, s[100:101] nt
	v_add_u32_e32 v68, 0x8000, v69
	global_load_dwordx4 v[6:9], v68, s[100:101] nt
	v_add_u32_e32 v67, 0x10000, v69
	global_load_dwordx4 v[10:13], v67, s[100:101] nt
	v_add_u32_e32 v68, 0x18000, v69
	global_load_dwordx4 v[14:17], v68, s[100:101] nt
	v_add_u32_e32 v67, 0x20000, v69
	global_load_dwordx4 v[18:21], v67, s[100:101] nt
	v_add_u32_e32 v68, 0x28000, v69
	global_load_dwordx4 v[22:25], v68, s[100:101] nt
	v_add_u32_e32 v67, 0x30000, v69
	global_load_dwordx4 v[26:29], v67, s[100:101] nt
	v_add_u32_e32 v68, 0x38000, v69
	global_load_dwordx4 v[30:33], v68, s[100:101] nt
	v_add_u32_e32 v67, 0x40000, v69
	global_load_dwordx4 v[34:37], v67, s[100:101] nt
	v_add_u32_e32 v68, 0x48000, v69
	global_load_dwordx4 v[38:41], v68, s[100:101] nt
	v_add_u32_e32 v67, 0x50000, v69
	global_load_dwordx4 v[42:45], v67, s[100:101] nt
	v_add_u32_e32 v68, 0x58000, v69
	global_load_dwordx4 v[46:49], v68, s[100:101] nt
	v_add_u32_e32 v67, 0x60000, v69
	global_load_dwordx4 v[50:53], v67, s[100:101] nt
	v_add_u32_e32 v68, 0x68000, v69
	global_load_dwordx4 v[54:57], v68, s[100:101] nt
	v_add_u32_e32 v67, 0x70000, v69
	global_load_dwordx4 v[58:61], v67, s[100:101] nt
	v_add_u32_e32 v68, 0x78000, v69
	global_load_dwordx4 v[62:65], v68, s[100:101] nt
	s_waitcnt vmcnt(15)
	ds_write_b32 v70, v2
	ds_write_b32 v70, v3 offset:4
	ds_write_b32 v70, v4 offset:8
	ds_write_b32 v70, v5 offset:12
	s_waitcnt vmcnt(14)
	ds_write_b32 v70, v6 offset:1040
	ds_write_b32 v70, v7 offset:1044
	ds_write_b32 v70, v8 offset:1048
	ds_write_b32 v70, v9 offset:1052
	s_waitcnt vmcnt(13)
	ds_write_b32 v70, v10 offset:2080
	ds_write_b32 v70, v11 offset:2084
	ds_write_b32 v70, v12 offset:2088
	ds_write_b32 v70, v13 offset:2092
	s_waitcnt vmcnt(12)
	ds_write_b32 v70, v14 offset:3120
	ds_write_b32 v70, v15 offset:3124
	ds_write_b32 v70, v16 offset:3128
	ds_write_b32 v70, v17 offset:3132
	s_waitcnt vmcnt(11)
	ds_write_b32 v70, v18 offset:4160
	ds_write_b32 v70, v19 offset:4164
	ds_write_b32 v70, v20 offset:4168
	ds_write_b32 v70, v21 offset:4172
	s_waitcnt vmcnt(10)
	ds_write_b32 v70, v22 offset:5200
	ds_write_b32 v70, v23 offset:5204
	ds_write_b32 v70, v24 offset:5208
	ds_write_b32 v70, v25 offset:5212
	s_waitcnt vmcnt(9)
	ds_write_b32 v70, v26 offset:6240
	ds_write_b32 v70, v27 offset:6244
	ds_write_b32 v70, v28 offset:6248
	ds_write_b32 v70, v29 offset:6252
	s_waitcnt vmcnt(8)
	ds_write_b32 v70, v30 offset:7280
	ds_write_b32 v70, v31 offset:7284
	ds_write_b32 v70, v32 offset:7288
	ds_write_b32 v70, v33 offset:7292
	s_waitcnt vmcnt(7)
	ds_write_b32 v70, v34 offset:8320
	ds_write_b32 v70, v35 offset:8324
	ds_write_b32 v70, v36 offset:8328
	ds_write_b32 v70, v37 offset:8332
	s_waitcnt vmcnt(6)
	ds_write_b32 v70, v38 offset:9360
	ds_write_b32 v70, v39 offset:9364
	ds_write_b32 v70, v40 offset:9368
	ds_write_b32 v70, v41 offset:9372
	s_waitcnt vmcnt(5)
	ds_write_b32 v70, v42 offset:10400
	ds_write_b32 v70, v43 offset:10404
	ds_write_b32 v70, v44 offset:10408
	ds_write_b32 v70, v45 offset:10412
	s_waitcnt vmcnt(4)
	ds_write_b32 v70, v46 offset:11440
	ds_write_b32 v70, v47 offset:11444
	ds_write_b32 v70, v48 offset:11448
	ds_write_b32 v70, v49 offset:11452
	s_waitcnt vmcnt(3)
; #define LAS __attribute__((address_space(3)))
; __device__ __forceinline__ unsigned cvtpk(float lo, float hi) { f32x2_t v = {lo, hi}; bf16x2_t b = __builtin_convertvector(v, bf16x2_t); return __builtin_bit_cast(unsigned, b); }
; __device__ __forceinline__ void tr_all(const float* const* in, unsigned char* ws, LAS float* scr, int gw, int ngw, int lane, const TrRanges rg) {
;     ...
;         const LAS float* rp = scr + (8 * (lane & 7)) * 65 + (lane >> 3);
; #pragma unroll
;         for (int j = 0; j < 8; ++j) { const LAS float* s = rp + 8 * j;
;             u32x4 o; o.x = cvtpk(s[0 * 65] * g0[0], s[1 * 65] * g0[1]); o.y = cvtpk(s[2 * 65] * g0[2], s[3 * 65] * g0[3]);
;             o.z = cvtpk(s[4 * 65] * g1[0], s[5 * 65] * g1[1]); o.w = cvtpk(s[6 * 65] * g1[2], s[7 * 65] * g1[3]);
;             if (cur.nts) __builtin_nontemporal_store(o, (u32x4*)(cur.dst + (size_t)(8 * j) * cur.K)); else *(u32x4*)(cur.dst + (size_t)(8 * j) * cur.K) = o; }
;         asm volatile("s_waitcnt lgkmcnt(0)" ::: "memory");
	ds_write_b32 v70, v50 offset:12480
	ds_write_b32 v70, v51 offset:12484
	ds_write_b32 v70, v52 offset:12488
	ds_write_b32 v70, v53 offset:12492
	s_waitcnt vmcnt(2)
	ds_write_b32 v70, v54 offset:13520
	ds_write_b32 v70, v55 offset:13524
	ds_write_b32 v70, v56 offset:13528
	ds_write_b32 v70, v57 offset:13532
	s_waitcnt vmcnt(1)
	ds_write_b32 v70, v58 offset:14560
	ds_write_b32 v70, v59 offset:14564
	ds_write_b32 v70, v60 offset:14568
	ds_write_b32 v70, v61 offset:14572
	s_waitcnt vmcnt(0)
	ds_write_b32 v70, v62 offset:15600
	ds_write_b32 v70, v63 offset:15604
	ds_write_b32 v70, v64 offset:15608
	ds_write_b32 v70, v65 offset:15612
	s_add_u32 s100, s84, 0x8700000
	s_addc_u32 s101, s85, 0
	s_waitcnt lgkmcnt(0)
	ds_read_b32 v2, v71
	ds_read_b32 v3, v71 offset:260
	ds_read_b32 v4, v71 offset:520
	ds_read_b32 v5, v71 offset:780
	ds_read_b32 v6, v71 offset:1040
	ds_read_b32 v7, v71 offset:1300
	ds_read_b32 v8, v71 offset:1560
	ds_read_b32 v9, v71 offset:1820
	ds_read_b32 v10, v71 offset:32
	ds_read_b32 v11, v71 offset:292
	ds_read_b32 v12, v71 offset:552
	ds_read_b32 v13, v71 offset:812
	ds_read_b32 v14, v71 offset:1072
	ds_read_b32 v15, v71 offset:1332
	ds_read_b32 v16, v71 offset:1592
	ds_read_b32 v17, v71 offset:1852
	ds_read_b32 v18, v71 offset:64
	ds_read_b32 v19, v71 offset:324
	ds_read_b32 v20, v71 offset:584
	ds_read_b32 v21, v71 offset:844
	ds_read_b32 v22, v71 offset:1104
	ds_read_b32 v23, v71 offset:1364
	ds_read_b32 v24, v71 offset:1624
	ds_read_b32 v25, v71 offset:1884
	ds_read_b32 v26, v71 offset:96
	ds_read_b32 v27, v71 offset:356
	ds_read_b32 v28, v71 offset:616
	ds_read_b32 v29, v71 offset:876
	ds_read_b32 v30, v71 offset:1136
	ds_read_b32 v31, v71 offset:1396
	ds_read_b32 v32, v71 offset:1656
	ds_read_b32 v33, v71 offset:1916
	ds_read_b32 v34, v71 offset:128
	ds_read_b32 v35, v71 offset:388
	ds_read_b32 v36, v71 offset:648
	ds_read_b32 v37, v71 offset:908
	ds_read_b32 v38, v71 offset:1168
	ds_read_b32 v39, v71 offset:1428
	ds_read_b32 v40, v71 offset:1688
	ds_read_b32 v41, v71 offset:1948
	ds_read_b32 v42, v71 offset:160
	ds_read_b32 v43, v71 offset:420
	ds_read_b32 v44, v71 offset:680
	ds_read_b32 v45, v71 offset:940
	ds_read_b32 v46, v71 offset:1200
	ds_read_b32 v47, v71 offset:1460
	ds_read_b32 v48, v71 offset:1720
	ds_read_b32 v49, v71 offset:1980
	ds_read_b32 v50, v71 offset:192
	ds_read_b32 v51, v71 offset:452
	ds_read_b32 v52, v71 offset:712
	ds_read_b32 v53, v71 offset:972
	ds_read_b32 v54, v71 offset:1232
	ds_read_b32 v55, v71 offset:1492
	ds_read_b32 v56, v71 offset:1752
	ds_read_b32 v57, v71 offset:2012
	ds_read_b32 v58, v71 offset:224
	ds_read_b32 v59, v71 offset:484
	ds_read_b32 v60, v71 offset:744
	ds_read_b32 v61, v71 offset:1004
	ds_read_b32 v62, v71 offset:1264
	ds_read_b32 v63, v71 offset:1524
	ds_read_b32 v64, v71 offset:1784
	ds_read_b32 v65, v71 offset:2044
	s_waitcnt lgkmcnt(15)
	v_cvt_pk_bf16_f32 v192, v2, v3
	v_cvt_pk_bf16_f32 v193, v4, v5
	v_cvt_pk_bf16_f32 v194, v6, v7
	v_cvt_pk_bf16_f32 v195, v8, v9
	global_store_dwordx4 v72, v[192:195], s[100:101] nt
	s_waitcnt lgkmcnt(15)
	v_cvt_pk_bf16_f32 v196, v10, v11
	v_cvt_pk_bf16_f32 v197, v12, v13
	v_cvt_pk_bf16_f32 v198, v14, v15
	v_cvt_pk_bf16_f32 v199, v16, v17
	v_add_u32_e32 v68, 0x2000, v72
	global_store_dwordx4 v68, v[196:199], s[100:101] nt
	s_waitcnt lgkmcnt(15)
	v_cvt_pk_bf16_f32 v200, v18, v19
	v_cvt_pk_bf16_f32 v201, v20, v21
	v_cvt_pk_bf16_f32 v202, v22, v23
	v_cvt_pk_bf16_f32 v203, v24, v25
	v_add_u32_e32 v67, 0x4000, v72
	global_store_dwordx4 v67, v[200:203], s[100:101] nt
	s_waitcnt lgkmcnt(15)
	v_cvt_pk_bf16_f32 v204, v26, v27
	v_cvt_pk_bf16_f32 v205, v28, v29
	v_cvt_pk_bf16_f32 v206, v30, v31
	v_cvt_pk_bf16_f32 v207, v32, v33
	v_add_u32_e32 v68, 0x6000, v72
	global_store_dwordx4 v68, v[204:207], s[100:101] nt
	s_waitcnt lgkmcnt(15)
	v_cvt_pk_bf16_f32 v208, v34, v35
	v_cvt_pk_bf16_f32 v209, v36, v37
	v_cvt_pk_bf16_f32 v210, v38, v39
	v_cvt_pk_bf16_f32 v211, v40, v41
	v_add_u32_e32 v67, 0x8000, v72
	global_store_dwordx4 v67, v[208:211], s[100:101] nt
	s_waitcnt lgkmcnt(15)
	v_cvt_pk_bf16_f32 v212, v42, v43
	v_cvt_pk_bf16_f32 v213, v44, v45
	v_cvt_pk_bf16_f32 v214, v46, v47
	v_cvt_pk_bf16_f32 v215, v48, v49
	v_add_u32_e32 v68, 0xa000, v72
	global_store_dwordx4 v68, v[212:215], s[100:101] nt
	s_waitcnt lgkmcnt(8)
	v_cvt_pk_bf16_f32 v216, v50, v51
	v_cvt_pk_bf16_f32 v217, v52, v53
	v_cvt_pk_bf16_f32 v218, v54, v55
	v_cvt_pk_bf16_f32 v219, v56, v57
	v_add_u32_e32 v67, 0xc000, v72
	global_store_dwordx4 v67, v[216:219], s[100:101] nt
	s_waitcnt lgkmcnt(0)
	v_cvt_pk_bf16_f32 v220, v58, v59
	v_cvt_pk_bf16_f32 v221, v60, v61
	v_cvt_pk_bf16_f32 v222, v62, v63
	v_cvt_pk_bf16_f32 v223, v64, v65
	v_add_u32_e32 v68, 0xe000, v72
	global_store_dwordx4 v68, v[220:223], s[100:101] nt
